# GEMM call prologues: second batch of six LDS-DMA loads (K-tile 1) issued before the first wait+barrier instead of after it (vmcnt 2->8), all nine instances; on top of v25
# baseline (speedup 1.0000x reference)
; #define PG8_STAGE(bufoff, gbase, voff) do { _Pragma("unroll") for (int _i = 0; _i < 2; ++_i) \
;         __builtin_amdgcn_global_load_lds((const unsigned*)((const char*)(gbase) + (voff)[_i]), (PG8_LAS unsigned*)(lds + (bufoff) + ldsw + _i * 8192), 16, 0, 0); } while (0)
; #define PG8_WAIT_V(n) asm volatile("s_waitcnt vmcnt(" #n ")" ::: "memory")
; #define PG8_BAR __builtin_amdgcn_s_barrier()
; template <class Epi, class Sched, bool ALIGN_EPI = false, bool SP2 = false>
; __device__ __forceinline__ void gemm_phase(PG8_LAS unsigned char* lds, const Gemm g, const Sched& S, const Epi& E) {
;     ...
;     for (int i = 0; i < 2; ++i) { int R, C; stage_rc(tid * 16 + i * 8192, R, C); const int Rb = Epi::PERM ? ((R & ~31) + perm32(R & 31)) : R;
;         voffA[i] = (unsigned)(R * K + C) * 2u; voffB[i] = (unsigned)(Rb * K + C) * 2u; }
;     const size_t kstep = (size_t)(BK * 2);
;     const size_t hstep = (size_t)HALF * K * 2;
;     const size_t tstep = 2 * hstep;
;     const unsigned ldsw = (unsigned)wid * 1024u;
;     const int aoff = lds_byte(wr * 64 + fr, fq * 8), boff = lds_byte(wc * 32 + fr, fq * 8);
;     ...
;     if constexpr (SP2) {
;         PG8_STAGE(PG8_SB(0, 0), cB, voffB); PG8_STAGE(PG8_SB(0, 1), cB + hstep, voffB); PG8_STAGE(PG8_SA(0, 0), cA, voffA); PG8_STAGE(PG8_SA(0, 1), cA + hstep, voffA);
;         if (wr == 1) PG8_BAR;
;         PG8_WAIT_V(2); PG8_BAR;
;         PG8_STAGE(PG8_SB(1, 0), cB + kstep, voffB); PG8_STAGE(PG8_SA(1, 0), cA + kstep, voffA); PG8_STAGE(PG8_SB(1, 1), cB + hstep + kstep, voffB);
;         PG8_WAIT_V(6); PG8_BAR;
.LBB0_55:
	v_lshrrev_b32_e32 v1, 1, v1
	v_or_b32_e32 v33, s38, v16
	v_and_b32_e32 v17, 24, v1
	s_sext_i32_i8 s3, s0
	v_lshlrev_b32_e32 v1, 6, v33
	v_lshlrev_b32_e32 v18, 1, v17
	s_movk_i32 s0, 0x3c0
	v_lshlrev_b32_e32 v19, 2, v33
	v_and_or_b32 v1, v1, s0, v18
	s_lshl_b32 s0, s2, 13
	v_and_b32_e32 v19, 32, v19
	v_bitop3_b32 v19, v1, s0, v19 bitop3:0xde
	s_lshl_b32 s0, s7, 5
	s_and_b32 s2, s0, 0x60
	v_lshl_or_b32 v1, v16, 6, v18
	s_lshl_b32 s0, s2, 7
	v_and_b32_e32 v16, 32, v0
	s_add_i32 m0, s8, 0x18000
	v_lshl_add_u64 v[6:7], v[6:7], 0, s[34:35]
	v_bitop3_b32 v139, v1, s0, v16 bitop3:0xde
	global_load_lds_dwordx4 v[6:7], off
	v_lshl_add_u64 v[4:5], v[4:5], 0, s[34:35]
	s_add_i32 m0, s8, 0x1a000
	s_add_i32 s0, s8, 0x8000
	s_add_i32 s97, s8, 0xa000
	global_load_lds_dwordx4 v[4:5], off
	v_lshl_add_u64 v[2:3], v[2:3], 0, s[34:35]
	s_mov_b32 m0, s0
	s_add_u32 s38, s90, 0x40080
	global_load_lds_dwordx4 v[2:3], off
	v_lshl_add_u64 v[2:3], v[8:9], 0, s[34:35]
	s_mov_b32 m0, s97
	s_addc_u32 s39, s91, 0
	global_load_lds_dwordx4 v[2:3], off
	s_add_i32 m0, s8, 0x1c000
	v_lshl_add_u64 v[2:3], s[38:39], 0, v[132:133]
	global_load_lds_dwordx4 v[2:3], off
	v_lshl_add_u64 v[2:3], s[38:39], 0, v[136:137]
	s_add_i32 m0, s8, 0x1e000
	s_cmpk_lt_u32 s4, 0x100
	global_load_lds_dwordx4 v[2:3], off
	s_cselect_b64 s[38:39], -1, 0
	s_add_u32 s44, s66, s44
	s_addc_u32 s45, s67, s45
	v_mov_b32_e32 v1, v32
	v_lshl_add_u64 v[144:145], s[44:45], 0, v[0:1]
	v_lshlrev_b32_e32 v0, 14, v13
	v_and_b32_e32 v0, 0xffff8000, v0
	v_lshl_add_u32 v0, v14, 11, v0
	v_and_b32_e32 v1, 1, v13
	v_lshl_or_b32 v0, v1, 6, v0
	v_lshl_add_u32 v148, v15, 1, v0
	v_lshlrev_b32_e32 v0, 14, v10
	v_and_b32_e32 v0, 0xffff8000, v0
	s_waitcnt vmcnt(8)
	s_barrier
	s_waitcnt vmcnt(6)
	v_lshl_add_u32 v0, v11, 11, v0
	v_and_b32_e32 v1, 1, v10
	v_lshl_or_b32 v0, v1, 6, v0
	v_or_b32_e32 v141, s2, v17
	v_mov_b32_e32 v149, v32
	v_lshl_add_u32 v150, v12, 1, v0
	v_mov_b32_e32 v151, v32
	s_mov_b32 s2, 0
	v_add_u32_e32 v143, 0, v19
	s_barrier
	s_branch .LBB0_58

; #define PG8_STAGE(bufoff, gbase, voff) do { _Pragma("unroll") for (int _i = 0; _i < 2; ++_i) \
;         __builtin_amdgcn_global_load_lds((const unsigned*)((const char*)(gbase) + (voff)[_i]), (PG8_LAS unsigned*)(lds + (bufoff) + ldsw + _i * 8192), 16, 0, 0); } while (0)
; #define PG8_WAIT_V(n) asm volatile("s_waitcnt vmcnt(" #n ")" ::: "memory")
; #define PG8_BAR __builtin_amdgcn_s_barrier()
; template <class Epi, class Sched, bool ALIGN_EPI = false, bool SP2 = false>
; __device__ __forceinline__ void gemm_phase(PG8_LAS unsigned char* lds, const Gemm g, const Sched& S, const Epi& E) {
;     ...
;     for (int i = 0; i < 2; ++i) { int R, C; stage_rc(tid * 16 + i * 8192, R, C); const int Rb = Epi::PERM ? ((R & ~31) + perm32(R & 31)) : R;
;         voffA[i] = (unsigned)(R * K + C) * 2u; voffB[i] = (unsigned)(Rb * K + C) * 2u; }
;     const size_t kstep = (size_t)(BK * 2);
;     const size_t hstep = (size_t)HALF * K * 2;
;     const size_t tstep = 2 * hstep;
;     const unsigned ldsw = (unsigned)wid * 1024u;
;     const int aoff = lds_byte(wr * 64 + fr, fq * 8), boff = lds_byte(wc * 32 + fr, fq * 8);
;     ...
;     if constexpr (SP2) {
;         PG8_STAGE(PG8_SB(0, 0), cB, voffB); PG8_STAGE(PG8_SB(0, 1), cB + hstep, voffB); PG8_STAGE(PG8_SA(0, 0), cA, voffA); PG8_STAGE(PG8_SA(0, 1), cA + hstep, voffA);
;         if (wr == 1) PG8_BAR;
;         PG8_WAIT_V(2); PG8_BAR;
;         PG8_STAGE(PG8_SB(1, 0), cB + kstep, voffB); PG8_STAGE(PG8_SA(1, 0), cA + kstep, voffA); PG8_STAGE(PG8_SB(1, 1), cB + hstep + kstep, voffB);
;         PG8_WAIT_V(6); PG8_BAR;
.LBB0_80:
	v_lshrrev_b32_e32 v16, 1, v12
	v_and_b32_e32 v16, 24, v16
	v_and_b32_e32 v15, 15, v12
	v_lshlrev_b32_e32 v17, 1, v16
	v_lshlrev_b32_e32 v12, 2, v12
	s_sext_i32_i16 s45, s0
	v_lshl_or_b32 v33, s3, 6, v15
	v_lshl_or_b32 v15, v15, 6, v17
	s_lshl_b32 s0, s3, 13
	v_and_b32_e32 v12, 32, v12
	v_bitop3_b32 v17, v15, s0, v12 bitop3:0xde
	s_lshl_b32 s0, s5, 5
	s_and_b32 s5, s0, 0x60
	s_lshl_b32 s0, s5, 7
	s_add_i32 m0, s9, 0x18000
	v_lshl_add_u64 v[4:5], v[4:5], 0, s[34:35]
	v_bitop3_b32 v170, v15, s0, v12 bitop3:0xde
	global_load_lds_dwordx4 v[4:5], off
	v_lshl_add_u64 v[2:3], v[2:3], 0, s[34:35]
	s_add_i32 m0, s9, 0x1a000
	s_add_i32 s0, s9, 0x8000
	s_add_i32 s3, s9, 0xa000
	global_load_lds_dwordx4 v[2:3], off
	v_lshl_add_u64 v[0:1], v[0:1], 0, s[34:35]
	s_mov_b32 m0, s0
	s_add_u32 s38, s46, 0x40080
	global_load_lds_dwordx4 v[0:1], off
	v_lshl_add_u64 v[0:1], v[6:7], 0, s[34:35]
	s_mov_b32 m0, s3
	s_addc_u32 s39, s47, 0
	global_load_lds_dwordx4 v[0:1], off
	s_add_i32 m0, s9, 0x1c000
	v_lshl_add_u64 v[0:1], s[38:39], 0, v[148:149]
	global_load_lds_dwordx4 v[0:1], off
	v_lshl_add_u64 v[0:1], s[38:39], 0, v[152:153]
	s_add_i32 m0, s9, 0x1e000
	s_cmpk_lt_u32 s4, 0x100
	global_load_lds_dwordx4 v[0:1], off
	v_lshlrev_b32_e32 v0, 14, v11
	v_and_b32_e32 v0, 0xffff8000, v0
	v_lshl_add_u32 v0, v13, 11, v0
	v_and_b32_e32 v1, 1, v11
	v_lshl_or_b32 v0, v1, 6, v0
	v_lshl_add_u32 v154, v14, 1, v0
	v_lshlrev_b32_e32 v0, 14, v8
	v_and_b32_e32 v0, 0xffff8000, v0
	s_waitcnt vmcnt(8)
	s_barrier
	s_waitcnt vmcnt(6)
	v_lshl_add_u32 v0, v9, 11, v0
	v_and_b32_e32 v1, 1, v8
	v_lshl_or_b32 v0, v1, 6, v0
	s_cselect_b64 s[38:39], -1, 0
	v_or_b32_e32 v171, s5, v16
	v_mov_b32_e32 v155, v32
	v_lshl_add_u32 v156, v10, 1, v0
	v_mov_b32_e32 v157, v32
	s_mov_b32 s4, 0
	v_add_u32_e32 v172, 0, v17
	s_barrier
	s_branch .LBB0_83

; #define PG8_STAGE(bufoff, gbase, voff) do { _Pragma("unroll") for (int _i = 0; _i < 2; ++_i) \
;         __builtin_amdgcn_global_load_lds((const unsigned*)((const char*)(gbase) + (voff)[_i]), (PG8_LAS unsigned*)(lds + (bufoff) + ldsw + _i * 8192), 16, 0, 0); } while (0)
; #define PG8_WAIT_V(n) asm volatile("s_waitcnt vmcnt(" #n ")" ::: "memory")
; #define PG8_BAR __builtin_amdgcn_s_barrier()
; template <class Epi, class Sched, bool ALIGN_EPI = false, bool SP2 = false>
; __device__ __forceinline__ void gemm_phase(PG8_LAS unsigned char* lds, const Gemm g, const Sched& S, const Epi& E) {
;     ...
;     for (int i = 0; i < 2; ++i) { int R, C; stage_rc(tid * 16 + i * 8192, R, C); const int Rb = Epi::PERM ? ((R & ~31) + perm32(R & 31)) : R;
;         voffA[i] = (unsigned)(R * K + C) * 2u; voffB[i] = (unsigned)(Rb * K + C) * 2u; }
;     const size_t kstep = (size_t)(BK * 2);
;     const size_t hstep = (size_t)HALF * K * 2;
;     const size_t tstep = 2 * hstep;
;     const unsigned ldsw = (unsigned)wid * 1024u;
;     const int aoff = lds_byte(wr * 64 + fr, fq * 8), boff = lds_byte(wc * 32 + fr, fq * 8);
;     ...
;     if constexpr (SP2) {
;         PG8_STAGE(PG8_SB(0, 0), cB, voffB); PG8_STAGE(PG8_SB(0, 1), cB + hstep, voffB); PG8_STAGE(PG8_SA(0, 0), cA, voffA); PG8_STAGE(PG8_SA(0, 1), cA + hstep, voffA);
;         if (wr == 1) PG8_BAR;
;         PG8_WAIT_V(2); PG8_BAR;
;         PG8_STAGE(PG8_SB(1, 0), cB + kstep, voffB); PG8_STAGE(PG8_SA(1, 0), cA + kstep, voffA); PG8_STAGE(PG8_SB(1, 1), cB + hstep + kstep, voffB);
;         PG8_WAIT_V(6); PG8_BAR;
.LBB0_107:
	v_lshrrev_b32_e32 v1, 1, v1
	v_or_b32_e32 v33, s86, v16
	v_and_b32_e32 v17, 24, v1
	s_sext_i32_i8 s4, s0
	v_lshlrev_b32_e32 v1, 6, v33
	v_lshlrev_b32_e32 v18, 1, v17
	s_movk_i32 s0, 0x3c0
	v_lshlrev_b32_e32 v19, 2, v33
	v_and_or_b32 v1, v1, s0, v18
	s_lshl_b32 s0, s7, 13
	v_and_b32_e32 v19, 32, v19
	v_bitop3_b32 v19, v1, s0, v19 bitop3:0xde
	s_lshl_b32 s0, s8, 5
	s_and_b32 s7, s0, 0x60
	v_lshl_or_b32 v1, v16, 6, v18
	s_lshl_b32 s0, s7, 7
	v_and_b32_e32 v16, 32, v0
	s_add_i32 m0, s39, 0x18000
	v_lshl_add_u64 v[6:7], v[6:7], 0, s[34:35]
	v_bitop3_b32 v145, v1, s0, v16 bitop3:0xde
	global_load_lds_dwordx4 v[6:7], off
	v_lshl_add_u64 v[4:5], v[4:5], 0, s[34:35]
	s_add_i32 m0, s39, 0x1a000
	s_add_i32 s0, s39, 0x8000
	s_add_i32 s86, s39, 0xa000
	global_load_lds_dwordx4 v[4:5], off
	v_lshl_add_u64 v[2:3], v[2:3], 0, s[34:35]
	s_mov_b32 m0, s0
	s_add_u32 s8, s46, 0x40080
	global_load_lds_dwordx4 v[2:3], off
	v_lshl_add_u64 v[2:3], v[8:9], 0, s[34:35]
	s_mov_b32 m0, s86
	s_addc_u32 s9, s47, 0
	global_load_lds_dwordx4 v[2:3], off
	s_add_i32 m0, s39, 0x1c000
	v_lshl_add_u64 v[2:3], s[8:9], 0, v[132:133]
	global_load_lds_dwordx4 v[2:3], off
	v_lshl_add_u64 v[2:3], s[8:9], 0, v[136:137]
	s_add_i32 m0, s39, 0x1e000
	s_cmpk_lt_u32 s5, 0x100
	global_load_lds_dwordx4 v[2:3], off
	s_cselect_b64 s[8:9], -1, 0
	v_writelane_b32 v254, s8, 51
	v_mov_b32_e32 v1, v32
	s_waitcnt vmcnt(8)
	s_barrier
	s_waitcnt vmcnt(6)
	v_or_b32_e32 v147, s7, v17
	v_writelane_b32 v254, s9, 52
	s_add_u32 s8, s66, s50
	s_addc_u32 s9, s67, s51
	s_waitcnt vmcnt(0)
	v_lshl_add_u64 v[138:139], s[8:9], 0, v[0:1]
	v_lshlrev_b32_e32 v0, 14, v13
	v_and_b32_e32 v0, 0xffff8000, v0
	v_lshl_add_u32 v0, v14, 11, v0
	v_and_b32_e32 v1, 1, v13
	v_lshl_or_b32 v0, v1, 6, v0
	v_lshl_add_u32 v140, v15, 1, v0
	v_lshlrev_b32_e32 v0, 14, v10
	v_and_b32_e32 v0, 0xffff8000, v0
	v_lshl_add_u32 v0, v11, 11, v0
	v_and_b32_e32 v1, 1, v10
	v_lshl_or_b32 v0, v1, 6, v0
	v_mov_b32_e32 v141, v32
	v_lshl_add_u32 v142, v12, 1, v0
	v_mov_b32_e32 v143, v32
	s_mov_b32 s9, 0
	v_add_u32_e32 v149, 0, v19
	s_barrier
	s_branch .LBB0_110

; #define PG8_STAGE(bufoff, gbase, voff) do { _Pragma("unroll") for (int _i = 0; _i < 2; ++_i) \
;         __builtin_amdgcn_global_load_lds((const unsigned*)((const char*)(gbase) + (voff)[_i]), (PG8_LAS unsigned*)(lds + (bufoff) + ldsw + _i * 8192), 16, 0, 0); } while (0)
; #define PG8_WAIT_V(n) asm volatile("s_waitcnt vmcnt(" #n ")" ::: "memory")
; #define PG8_BAR __builtin_amdgcn_s_barrier()
; template <class Epi, class Sched, bool ALIGN_EPI = false, bool SP2 = false>
; __device__ __forceinline__ void gemm_phase(PG8_LAS unsigned char* lds, const Gemm g, const Sched& S, const Epi& E) {
;     ...
;     for (int i = 0; i < 2; ++i) { int R, C; stage_rc(tid * 16 + i * 8192, R, C); const int Rb = Epi::PERM ? ((R & ~31) + perm32(R & 31)) : R;
;         voffA[i] = (unsigned)(R * K + C) * 2u; voffB[i] = (unsigned)(Rb * K + C) * 2u; }
;     const size_t kstep = (size_t)(BK * 2);
;     const size_t hstep = (size_t)HALF * K * 2;
;     const size_t tstep = 2 * hstep;
;     const unsigned ldsw = (unsigned)wid * 1024u;
;     const int aoff = lds_byte(wr * 64 + fr, fq * 8), boff = lds_byte(wc * 32 + fr, fq * 8);
;     ...
;     if constexpr (SP2) {
;         PG8_STAGE(PG8_SB(0, 0), cB, voffB); PG8_STAGE(PG8_SB(0, 1), cB + hstep, voffB); PG8_STAGE(PG8_SA(0, 0), cA, voffA); PG8_STAGE(PG8_SA(0, 1), cA + hstep, voffA);
;         if (wr == 1) PG8_BAR;
;         PG8_WAIT_V(2); PG8_BAR;
;         PG8_STAGE(PG8_SB(1, 0), cB + kstep, voffB); PG8_STAGE(PG8_SA(1, 0), cA + kstep, voffA); PG8_STAGE(PG8_SB(1, 1), cB + hstep + kstep, voffB);
;         PG8_WAIT_V(6); PG8_BAR;
.LBB0_134:
	v_mov_b32_e32 v149, v32
	v_lshrrev_b32_e32 v16, 1, v3
	v_lshl_add_u64 v[8:9], s[46:47], 0, v[148:149]
	v_mov_b32_e32 v153, v32
	v_and_b32_e32 v16, 24, v16
	s_lshl_b32 s2, s2, 5
	v_lshl_add_u64 v[10:11], s[46:47], 0, v[152:153]
	v_mov_b32_e32 v147, v32
	v_and_b32_e32 v7, 15, v3
	v_lshlrev_b32_e32 v17, 1, v16
	v_lshlrev_b32_e32 v3, 2, v3
	s_and_b32 s45, s2, 0x60
	s_add_i32 m0, s5, 0x18000
	v_lshl_add_u64 v[8:9], v[8:9], 0, s[34:35]
	v_lshl_add_u64 v[12:13], s[48:49], 0, v[146:147]
	v_mov_b32_e32 v151, v32
	v_lshl_or_b32 v17, v7, 6, v17
	s_lshl_b32 s3, s81, 13
	v_and_b32_e32 v3, 32, v3
	s_lshl_b32 s2, s45, 7
	global_load_lds_dwordx4 v[8:9], off
	v_lshl_add_u64 v[8:9], v[10:11], 0, s[34:35]
	s_add_i32 m0, s5, 0x1a000
	s_add_i32 s9, s5, 0x8000
	s_add_i32 s86, s5, 0xa000
	v_lshl_add_u64 v[14:15], s[48:49], 0, v[150:151]
	v_bitop3_b32 v176, v17, s2, v3 bitop3:0xde
	global_load_lds_dwordx4 v[8:9], off
	v_lshl_add_u64 v[8:9], v[12:13], 0, s[34:35]
	s_mov_b32 m0, s9
	s_add_u32 s2, s46, 0x40080
	v_bitop3_b32 v18, v17, s3, v3 bitop3:0xde
	global_load_lds_dwordx4 v[8:9], off
	v_lshl_add_u64 v[8:9], v[14:15], 0, s[34:35]
	s_mov_b32 m0, s86
	s_addc_u32 s3, s47, 0
	global_load_lds_dwordx4 v[8:9], off
	s_add_i32 m0, s5, 0x1c000
	v_lshl_add_u64 v[8:9], s[2:3], 0, v[148:149]
	global_load_lds_dwordx4 v[8:9], off
	v_lshl_add_u64 v[8:9], s[2:3], 0, v[152:153]
	s_add_i32 m0, s5, 0x1e000
	v_lshlrev_b32_e32 v3, 14, v4
	global_load_lds_dwordx4 v[8:9], off
	v_and_b32_e32 v3, 0xffff8000, v3
	v_lshl_add_u32 v3, v5, 11, v3
	v_and_b32_e32 v4, 1, v4
	v_lshl_or_b32 v3, v4, 6, v3
	s_cmpk_lt_u32 s7, 0x100
	v_lshl_add_u32 v154, v6, 1, v3
	v_lshlrev_b32_e32 v3, 14, v0
	s_cselect_b64 s[2:3], -1, 0
	v_and_b32_e32 v3, 0xffff8000, v3
	s_waitcnt vmcnt(8)
	s_barrier
	s_waitcnt vmcnt(6)
	v_writelane_b32 v254, s2, 51
	v_lshl_add_u32 v1, v1, 11, v3
	v_and_b32_e32 v0, 1, v0
	s_mov_b32 s50, s81
	v_writelane_b32 v254, s3, 52
	s_ashr_i32 s2, s81, 31
	v_lshl_or_b32 v0, v0, 6, v1
	v_lshl_or_b32 v33, s50, 6, v7
	s_mov_b32 s87, 0
	v_cmp_eq_u32_e64 s[38:39], 0, v7
	v_writelane_b32 v254, s2, 49
	v_or_b32_e32 v177, s45, v16
	v_mov_b32_e32 v155, v32
	v_lshl_add_u32 v156, v2, 1, v0
	v_mov_b32_e32 v157, v32
	v_add_u32_e32 v178, 0, v18
	s_barrier
	s_branch .LBB0_137

; #define PG8_STAGE(bufoff, gbase, voff) do { _Pragma("unroll") for (int _i = 0; _i < 2; ++_i) \
;         __builtin_amdgcn_global_load_lds((const unsigned*)((const char*)(gbase) + (voff)[_i]), (PG8_LAS unsigned*)(lds + (bufoff) + ldsw + _i * 8192), 16, 0, 0); } while (0)
; #define PG8_WAIT_V(n) asm volatile("s_waitcnt vmcnt(" #n ")" ::: "memory")
; #define PG8_BAR __builtin_amdgcn_s_barrier()
; template <class Epi, class Sched, bool ALIGN_EPI = false, bool SP2 = false>
; __device__ __forceinline__ void gemm_phase(PG8_LAS unsigned char* lds, const Gemm g, const Sched& S, const Epi& E) {
;     ...
;     for (int i = 0; i < 2; ++i) { int R, C; stage_rc(tid * 16 + i * 8192, R, C); const int Rb = Epi::PERM ? ((R & ~31) + perm32(R & 31)) : R;
;         voffA[i] = (unsigned)(R * K + C) * 2u; voffB[i] = (unsigned)(Rb * K + C) * 2u; }
;     const size_t kstep = (size_t)(BK * 2);
;     const size_t hstep = (size_t)HALF * K * 2;
;     const size_t tstep = 2 * hstep;
;     const unsigned ldsw = (unsigned)wid * 1024u;
;     const int aoff = lds_byte(wr * 64 + fr, fq * 8), boff = lds_byte(wc * 32 + fr, fq * 8);
;     ...
;     if constexpr (SP2) {
;         PG8_STAGE(PG8_SB(0, 0), cB, voffB); PG8_STAGE(PG8_SB(0, 1), cB + hstep, voffB); PG8_STAGE(PG8_SA(0, 0), cA, voffA); PG8_STAGE(PG8_SA(0, 1), cA + hstep, voffA);
;         if (wr == 1) PG8_BAR;
;         PG8_WAIT_V(2); PG8_BAR;
;         PG8_STAGE(PG8_SB(1, 0), cB + kstep, voffB); PG8_STAGE(PG8_SA(1, 0), cA + kstep, voffA); PG8_STAGE(PG8_SB(1, 1), cB + hstep + kstep, voffB);
;         PG8_WAIT_V(6); PG8_BAR;
.LBB0_354:
	v_bfe_u32 v20, v6, 4, 2
	v_mov_b32_e32 v133, v32
	v_mov_b32_e32 v137, v32
	v_and_b32_e32 v7, 15, v6
	v_lshlrev_b32_e32 v22, 4, v20
	v_lshlrev_b32_e32 v6, 2, v6
	v_lshl_add_u64 v[12:13], s[2:3], 0, v[132:133]
	v_lshl_add_u64 v[14:15], s[2:3], 0, v[136:137]
	s_and_b32 s81, s4, 3
	v_lshl_or_b32 v33, s5, 6, v7
	v_lshl_or_b32 v7, v7, 6, v22
	s_lshl_b32 s2, s5, 13
	v_and_b32_e32 v6, 32, v6
	v_lshl_add_u64 v[8:9], s[44:45], 0, v[132:133]
	v_bitop3_b32 v22, v7, s2, v6 bitop3:0xde
	s_lshl_b32 s2, s81, 12
	v_lshl_add_u64 v[10:11], s[44:45], 0, v[136:137]
	v_mov_b32_e32 v131, v32
	v_bitop3_b32 v146, v7, s2, v6 bitop3:0xde
	s_add_i32 m0, s51, 0x18000
	v_lshl_add_u64 v[6:7], v[8:9], 0, s[34:35]
	v_lshl_add_u64 v[16:17], s[46:47], 0, v[130:131]
	v_mov_b32_e32 v135, v32
	global_load_lds_dwordx4 v[6:7], off
	v_lshl_add_u64 v[6:7], v[10:11], 0, s[34:35]
	s_add_i32 m0, s51, 0x1a000
	s_add_i32 s85, s51, 0x8000
	v_lshl_add_u64 v[18:19], s[46:47], 0, v[134:135]
	global_load_lds_dwordx4 v[6:7], off
	v_lshl_add_u64 v[6:7], v[16:17], 0, s[34:35]
	s_mov_b32 m0, s85
	s_add_i32 s86, s51, 0xa000
	global_load_lds_dwordx4 v[6:7], off
	v_lshl_add_u64 v[6:7], v[18:19], 0, s[34:35]
	s_mov_b32 m0, s86
	s_lshr_b32 s82, s84, 6
	global_load_lds_dwordx4 v[6:7], off
	s_add_i32 m0, s51, 0x1c000
	v_lshl_add_u64 v[6:7], v[12:13], 0, s[34:35]
	global_load_lds_dwordx4 v[6:7], off
	v_lshl_add_u64 v[6:7], v[14:15], 0, s[34:35]
	s_add_i32 m0, s51, 0x1e000
	s_ashr_i32 s83, s53, 31
	global_load_lds_dwordx4 v[6:7], off
	s_waitcnt vmcnt(8)
	s_barrier
	s_waitcnt vmcnt(6)
	s_add_i32 s87, s82, -2
	v_add_u32_e32 v3, v5, v3
	v_add_u32_e32 v0, v2, v0
	v_lshlrev_b32_e32 v21, 3, v20
	s_cmpk_lt_u32 s40, 0x100
	v_add_lshl_u32 v4, v3, v4, 1
	v_mov_b32_e32 v5, v32
	v_add_lshl_u32 v0, v0, v1, 1
	v_mov_b32_e32 v1, v32
	v_lshl_or_b32 v147, s81, 5, v21
	s_cselect_b64 s[40:41], -1, 0
	s_mov_b32 s88, 0
	v_cmp_eq_u32_e64 s[2:3], 0, v20
	v_lshl_add_u64 v[138:139], s[8:9], 0, v[4:5]
	v_lshl_add_u64 v[140:141], s[8:9], 0, v[0:1]
	v_add_u32_e32 v148, 0, v22
	s_barrier
	s_branch .LBB0_357

; #define PG8_STAGE(bufoff, gbase, voff) do { _Pragma("unroll") for (int _i = 0; _i < 2; ++_i) \
;         __builtin_amdgcn_global_load_lds((const unsigned*)((const char*)(gbase) + (voff)[_i]), (PG8_LAS unsigned*)(lds + (bufoff) + ldsw + _i * 8192), 16, 0, 0); } while (0)
; #define PG8_WAIT_V(n) asm volatile("s_waitcnt vmcnt(" #n ")" ::: "memory")
; #define PG8_BAR __builtin_amdgcn_s_barrier()
;     __host__ __device__ bool next(int i, Unit& u) const {
;         if (i >= ni) return false;
;         const long L = (long)(i + i0) * G + c; if (L >= nwg) return false;
;         int wgid = (int)L; { const int q = nwg / NXCD, r = nwg % NXCD, xcd = wgid % NXCD, off = wgid / NXCD; wgid = (xcd < r ? xcd * (q + 1) : r * (q + 1) + (xcd - r) * q) + off; }
;         const int nig = WGM * nN, gid = wgid / nig, fm = gid * WGM, gsz = (nM - fm) < WGM ? (nM - fm) : WGM;
;         u.pm = fm + ((wgid % nig) % gsz); u.pn = (wgid % nig) / gsz; return true;
; template <class Epi, class Sched, bool ALIGN_EPI = false, bool SP2 = false>
; __device__ __forceinline__ void gemm_phase(PG8_LAS unsigned char* lds, const Gemm g, const Sched& S, const Epi& E) {
;     ...
;     if constexpr (SP2) {
;         PG8_STAGE(PG8_SB(0, 0), cB, voffB); PG8_STAGE(PG8_SB(0, 1), cB + hstep, voffB); PG8_STAGE(PG8_SA(0, 0), cA, voffA); PG8_STAGE(PG8_SA(0, 1), cA + hstep, voffA);
;         if (wr == 1) PG8_BAR;
;         PG8_WAIT_V(2); PG8_BAR;
;         PG8_STAGE(PG8_SB(1, 0), cB + kstep, voffB); PG8_STAGE(PG8_SA(1, 0), cA + kstep, voffA); PG8_STAGE(PG8_SB(1, 1), cB + hstep + kstep, voffB);
;         PG8_WAIT_V(6); PG8_BAR;
.LBB0_403:
	s_add_i32 m0, s82, 0x18000
	v_lshl_add_u64 v[0:1], v[0:1], 0, s[34:35]
	global_load_lds_dwordx4 v[0:1], off
	v_lshl_add_u64 v[0:1], v[2:3], 0, s[34:35]
	s_add_i32 m0, s82, 0x1a000
	s_add_i32 s90, s82, 0x8000
	global_load_lds_dwordx4 v[0:1], off
	v_lshl_add_u64 v[0:1], v[8:9], 0, s[34:35]
	s_mov_b32 m0, s90
	s_add_i32 s91, s82, 0xa000
	global_load_lds_dwordx4 v[0:1], off
	v_lshl_add_u64 v[0:1], v[10:11], 0, s[34:35]
	s_mov_b32 m0, s91
	v_bfe_u32 v19, v18, 4, 2
	global_load_lds_dwordx4 v[0:1], off
	s_add_i32 m0, s82, 0x1c000
	v_lshl_add_u64 v[0:1], v[4:5], 0, s[34:35]
	global_load_lds_dwordx4 v[0:1], off
	v_lshl_add_u64 v[0:1], v[6:7], 0, s[34:35]
	s_add_i32 m0, s82, 0x1e000
	v_and_b32_e32 v20, 15, v18
	global_load_lds_dwordx4 v[0:1], off
	v_lshlrev_b32_e32 v22, 4, v19
	v_lshlrev_b32_e32 v18, 2, v18
	s_and_b32 s89, s2, 3
	v_lshl_or_b32 v33, s3, 6, v20
	v_lshl_or_b32 v20, v20, 6, v22
	s_lshl_b32 s2, s3, 13
	v_and_b32_e32 v18, 32, v18
	v_bitop3_b32 v22, v20, s2, v18 bitop3:0xde
	s_lshl_b32 s2, s89, 12
	s_add_i32 s92, s85, -2
	s_cmpk_lt_u32 s42, 0x100
	s_cselect_b64 s[42:43], -1, 0
	s_cmpk_lt_i32 s53, 0x300
	s_cselect_b64 s[76:77], -1, 0
	s_add_i32 s4, s53, 0x100
	s_ashr_i32 s5, s4, 31
	s_lshr_b32 s5, s5, 29
	s_add_i32 s5, s4, s5
	s_ashr_i32 s38, s5, 3
	s_and_b32 s5, s5, -8
	s_sub_i32 s4, s4, s5
	s_lshl_b32 s5, s4, 7
	s_cmp_lt_i32 s4, 0
	s_mulk_i32 s4, 0x81
	s_cselect_b32 s4, s4, s5
	s_add_i32 s4, s4, s38
	s_ashr_i32 s5, s4, 31
	s_lshr_b32 s5, s5, 27
	s_add_i32 s5, s4, s5
	s_ashr_i32 s38, s5, 5
	s_and_b32 s5, s5, 0xffe0
	s_sub_i32 s4, s4, s5
	s_bfe_i32 s5, s4, 0x80000
	s_bfe_u32 s5, s5, 0x3000c
	s_add_i32 s5, s4, s5
	s_lshl_b32 s94, s38, 3
	s_and_b32 s38, s5, 0xf8
	s_sub_i32 s4, s4, s38
	v_add_u32_e32 v0, v17, v15
	s_sext_i32_i8 s4, s4
	v_add_lshl_u32 v0, v0, v16, 1
	v_mov_b32_e32 v1, v32
	s_waitcnt vmcnt(8)
	s_barrier
	s_waitcnt vmcnt(6)
	s_add_i32 s94, s94, s4
	s_bfe_i32 s4, s5, 0x80000
	v_lshl_add_u64 v[138:139], s[8:9], 0, v[0:1]
	v_add_u32_e32 v0, v14, v12
	v_lshlrev_b32_e32 v21, 3, v19
	s_sext_i32_i16 s4, s4
	v_add_lshl_u32 v0, v0, v13, 1
	v_bitop3_b32 v146, v20, s2, v18 bitop3:0xde
	v_lshl_or_b32 v147, s89, 5, v21
	s_mov_b32 s93, 0
	v_cmp_eq_u32_e64 s[2:3], 0, v19
	s_ashr_i32 s95, s4, 3
	v_lshl_add_u64 v[140:141], s[8:9], 0, v[0:1]
	v_add_u32_e32 v148, 0, v22
	s_mov_b64 s[78:79], s[46:47]
	s_barrier
	s_branch .LBB0_406

; #define PG8_STAGE(bufoff, gbase, voff) do { _Pragma("unroll") for (int _i = 0; _i < 2; ++_i) \
;         __builtin_amdgcn_global_load_lds((const unsigned*)((const char*)(gbase) + (voff)[_i]), (PG8_LAS unsigned*)(lds + (bufoff) + ldsw + _i * 8192), 16, 0, 0); } while (0)
; #define PG8_WAIT_V(n) asm volatile("s_waitcnt vmcnt(" #n ")" ::: "memory")
; #define PG8_BAR __builtin_amdgcn_s_barrier()
; template <class Epi, class Sched, bool ALIGN_EPI = false, bool SP2 = false>
; __device__ __forceinline__ void gemm_phase(PG8_LAS unsigned char* lds, const Gemm g, const Sched& S, const Epi& E) {
;     ...
;     for (int i = 0; i < 2; ++i) { int R, C; stage_rc(tid * 16 + i * 8192, R, C); const int Rb = Epi::PERM ? ((R & ~31) + perm32(R & 31)) : R;
;         voffA[i] = (unsigned)(R * K + C) * 2u; voffB[i] = (unsigned)(Rb * K + C) * 2u; }
;     const size_t kstep = (size_t)(BK * 2);
;     const size_t hstep = (size_t)HALF * K * 2;
;     const size_t tstep = 2 * hstep;
;     const unsigned ldsw = (unsigned)wid * 1024u;
;     const int aoff = lds_byte(wr * 64 + fr, fq * 8), boff = lds_byte(wc * 32 + fr, fq * 8);
;     ...
;     if constexpr (SP2) {
;         PG8_STAGE(PG8_SB(0, 0), cB, voffB); PG8_STAGE(PG8_SB(0, 1), cB + hstep, voffB); PG8_STAGE(PG8_SA(0, 0), cA, voffA); PG8_STAGE(PG8_SA(0, 1), cA + hstep, voffA);
;         if (wr == 1) PG8_BAR;
;         PG8_WAIT_V(2); PG8_BAR;
;         PG8_STAGE(PG8_SB(1, 0), cB + kstep, voffB); PG8_STAGE(PG8_SA(1, 0), cA + kstep, voffA); PG8_STAGE(PG8_SB(1, 1), cB + hstep + kstep, voffB);
;         PG8_WAIT_V(6); PG8_BAR;
.LBB0_437:
	v_lshrrev_b32_e32 v16, 1, v16
	v_or_b32_e32 v33, s4, v1
	v_and_b32_e32 v16, 24, v16
	v_lshlrev_b32_e32 v17, 6, v33
	v_lshlrev_b32_e32 v18, 1, v16
	s_movk_i32 s4, 0x3c0
	v_lshlrev_b32_e32 v19, 2, v33
	v_and_or_b32 v17, v17, s4, v18
	s_lshl_b32 s4, s76, 13
	v_and_b32_e32 v19, 32, v19
	v_bitop3_b32 v17, v17, s4, v19 bitop3:0xde
	s_lshl_b32 s4, s43, 5
	s_and_b32 s43, s4, 0x60
	s_add_i32 m0, s47, 0x18000
	v_lshl_add_u64 v[8:9], v[8:9], 0, s[34:35]
	v_lshl_or_b32 v1, v1, 6, v18
	s_lshl_b32 s4, s43, 7
	v_and_b32_e32 v18, 32, v0
	global_load_lds_dwordx4 v[8:9], off
	v_lshl_add_u64 v[6:7], v[6:7], 0, s[34:35]
	s_add_i32 m0, s47, 0x1a000
	s_add_i32 s93, s47, 0x8000
	s_add_i32 s94, s47, 0xa000
	v_bitop3_b32 v145, v1, s4, v18 bitop3:0xde
	global_load_lds_dwordx4 v[6:7], off
	v_lshl_add_u64 v[2:3], v[2:3], 0, s[34:35]
	s_mov_b32 m0, s93
	s_add_u32 s4, s48, 0x40080
	global_load_lds_dwordx4 v[2:3], off
	v_lshl_add_u64 v[2:3], v[4:5], 0, s[34:35]
	s_mov_b32 m0, s94
	s_addc_u32 s5, s49, 0
	global_load_lds_dwordx4 v[2:3], off
	s_add_i32 m0, s47, 0x1c000
	v_lshl_add_u64 v[2:3], s[4:5], 0, v[134:135]
	global_load_lds_dwordx4 v[2:3], off
	v_lshl_add_u64 v[2:3], s[4:5], 0, v[130:131]
	s_add_i32 m0, s47, 0x1e000
	s_cmpk_lt_u32 s42, 0x100
	global_load_lds_dwordx4 v[2:3], off
	s_cselect_b64 s[4:5], -1, 0
	s_add_u32 s38, s66, s40
	s_addc_u32 s39, s67, s41
	v_mov_b32_e32 v1, v32
	v_lshl_add_u64 v[138:139], s[38:39], 0, v[0:1]
	v_lshlrev_b32_e32 v0, 14, v10
	v_and_b32_e32 v0, 0xffff8000, v0
	v_lshl_add_u32 v0, v11, 11, v0
	v_and_b32_e32 v1, 1, v10
	v_lshl_or_b32 v0, v1, 6, v0
	v_lshl_add_u32 v140, v12, 1, v0
	v_lshlrev_b32_e32 v0, 14, v14
	v_and_b32_e32 v0, 0xffff8000, v0
	s_waitcnt vmcnt(8)
	s_barrier
	s_waitcnt vmcnt(6)
	v_lshl_add_u32 v0, v13, 11, v0
	v_and_b32_e32 v1, 1, v14
	v_lshl_or_b32 v0, v1, 6, v0
	v_or_b32_e32 v147, s43, v16
	v_mov_b32_e32 v141, v32
	v_lshl_add_u32 v142, v15, 1, v0
	v_mov_b32_e32 v143, v32
	s_mov_b32 s95, 0
	v_add_u32_e32 v149, 0, v17
	s_barrier
	s_branch .LBB0_440

; #define PG8_STAGE(bufoff, gbase, voff) do { _Pragma("unroll") for (int _i = 0; _i < 2; ++_i) \
;         __builtin_amdgcn_global_load_lds((const unsigned*)((const char*)(gbase) + (voff)[_i]), (PG8_LAS unsigned*)(lds + (bufoff) + ldsw + _i * 8192), 16, 0, 0); } while (0)
; #define PG8_WAIT_V(n) asm volatile("s_waitcnt vmcnt(" #n ")" ::: "memory")
; #define PG8_BAR __builtin_amdgcn_s_barrier()
;     __host__ __device__ bool next(int i, Unit& u) const {
;         if (i >= ni) return false;
;         const long L = (long)(i + i0) * G + c; if (L >= nwg) return false;
;         int wgid = (int)L; { const int q = nwg / NXCD, r = nwg % NXCD, xcd = wgid % NXCD, off = wgid / NXCD; wgid = (xcd < r ? xcd * (q + 1) : r * (q + 1) + (xcd - r) * q) + off; }
;         const int nig = WGM * nN, gid = wgid / nig, fm = gid * WGM, gsz = (nM - fm) < WGM ? (nM - fm) : WGM;
;         u.pm = fm + ((wgid % nig) % gsz); u.pn = (wgid % nig) / gsz; return true;
; template <class Epi, class Sched, bool ALIGN_EPI = false, bool SP2 = false>
; __device__ __forceinline__ void gemm_phase(PG8_LAS unsigned char* lds, const Gemm g, const Sched& S, const Epi& E) {
;     ...
;     if constexpr (SP2) {
;         PG8_STAGE(PG8_SB(0, 0), cB, voffB); PG8_STAGE(PG8_SB(0, 1), cB + hstep, voffB); PG8_STAGE(PG8_SA(0, 0), cA, voffA); PG8_STAGE(PG8_SA(0, 1), cA + hstep, voffA);
;         if (wr == 1) PG8_BAR;
;         PG8_WAIT_V(2); PG8_BAR;
;         PG8_STAGE(PG8_SB(1, 0), cB + kstep, voffB); PG8_STAGE(PG8_SA(1, 0), cA + kstep, voffA); PG8_STAGE(PG8_SB(1, 1), cB + hstep + kstep, voffB);
;         PG8_WAIT_V(6); PG8_BAR;
.LBB0_538:
	s_add_i32 m0, s78, 0x18000
	v_lshl_add_u64 v[0:1], v[0:1], 0, s[34:35]
	global_load_lds_dwordx4 v[0:1], off
	v_lshl_add_u64 v[0:1], v[2:3], 0, s[34:35]
	s_add_i32 m0, s78, 0x1a000
	s_add_i32 s83, s78, 0x8000
	global_load_lds_dwordx4 v[0:1], off
	v_lshl_add_u64 v[0:1], v[8:9], 0, s[34:35]
	s_mov_b32 m0, s83
	s_add_i32 s84, s78, 0xa000
	global_load_lds_dwordx4 v[0:1], off
	v_lshl_add_u64 v[0:1], v[10:11], 0, s[34:35]
	s_mov_b32 m0, s84
	v_bfe_u32 v19, v18, 4, 2
	global_load_lds_dwordx4 v[0:1], off
	s_add_i32 m0, s78, 0x1c000
	v_lshl_add_u64 v[0:1], v[4:5], 0, s[34:35]
	global_load_lds_dwordx4 v[0:1], off
	v_lshl_add_u64 v[0:1], v[6:7], 0, s[34:35]
	s_add_i32 m0, s78, 0x1e000
	v_and_b32_e32 v20, 15, v18
	global_load_lds_dwordx4 v[0:1], off
	v_lshlrev_b32_e32 v22, 4, v19
	v_lshlrev_b32_e32 v18, 2, v18
	s_and_b32 s82, s2, 3
	v_lshl_or_b32 v33, s3, 6, v20
	v_lshl_or_b32 v20, v20, 6, v22
	s_lshl_b32 s2, s3, 13
	v_and_b32_e32 v18, 32, v18
	v_bitop3_b32 v22, v20, s2, v18 bitop3:0xde
	s_lshl_b32 s2, s82, 12
	s_add_i32 s87, s85, -2
	s_cmpk_lt_u32 s40, 0x100
	s_mul_i32 s4, s36, 3
	s_cselect_b64 s[40:41], -1, 0
	s_add_u32 s4, s4, s53
	s_mul_hi_u32 s5, s36, 3
	s_addc_u32 s5, s5, s0
	s_ashr_i32 s0, s4, 31
	s_lshr_b32 s0, s0, 29
	s_add_i32 s0, s4, s0
	v_cmp_lt_i64_e64 s[48:49], s[4:5], v[168:169]
	s_ashr_i32 s5, s0, 3
	s_and_b32 s0, s0, -8
	s_sub_i32 s0, s4, s0
	s_lshl_b32 s4, s0, 7
	s_cmp_lt_i32 s0, 0
	s_mulk_i32 s0, 0x81
	s_cselect_b32 s0, s0, s4
	s_add_i32 s0, s0, s5
	s_ashr_i32 s4, s0, 31
	s_lshr_b32 s4, s4, 27
	s_add_i32 s4, s0, s4
	s_ashr_i32 s5, s4, 5
	s_lshl_b32 s5, s5, 3
	s_sub_i32 s42, 0x100, s5
	s_min_i32 s42, s42, 8
	s_abs_i32 s61, s42
	v_cvt_f32_u32_e32 v0, s61
	s_sub_i32 s72, 0, s61
	s_andn2_b32 s4, s4, 31
	s_sub_i32 s0, s0, s4
	v_rcp_iflag_f32_e32 v0, v0
	s_abs_i32 s43, s0
	s_xor_b32 s4, s0, s42
	s_ashr_i32 s4, s4, 31
	v_mul_f32_e32 v0, 0x4f7ffffe, v0
	v_cvt_u32_f32_e32 v0, v0
	v_mov_b32_e32 v1, v32
	s_waitcnt vmcnt(8)
	s_barrier
	s_waitcnt vmcnt(6)
	v_lshlrev_b32_e32 v21, 3, v19
	v_readfirstlane_b32 s73, v0
	s_mul_i32 s72, s72, s73
	s_mul_hi_u32 s72, s73, s72
	s_add_i32 s73, s73, s72
	s_mul_hi_u32 s72, s43, s73
	s_mul_i32 s73, s72, s61
	s_sub_i32 s43, s43, s73
	s_add_i32 s73, s72, 1
	s_sub_i32 s76, s43, s61
	s_cmp_ge_u32 s43, s61
	s_cselect_b32 s72, s73, s72
	s_cselect_b32 s43, s76, s43
	s_add_i32 s73, s72, 1
	s_cmp_ge_u32 s43, s61
	s_cselect_b32 s43, s73, s72
	s_xor_b32 s43, s43, s4
	v_add_u32_e32 v0, v17, v15
	s_sub_i32 s88, s43, s4
	v_add_lshl_u32 v0, v0, v16, 1
	s_mul_i32 s4, s88, s42
	v_lshl_add_u64 v[138:139], s[8:9], 0, v[0:1]
	v_add_u32_e32 v0, v14, v12
	s_sub_i32 s0, s0, s4
	v_add_lshl_u32 v0, v0, v13, 1
	s_waitcnt vmcnt(0)
	v_bitop3_b32 v146, v20, s2, v18 bitop3:0xde
	v_lshl_or_b32 v147, s82, 5, v21
	v_cmp_eq_u32_e64 s[2:3], 0, v19
	s_add_i32 s89, s5, s0
	v_lshl_add_u64 v[140:141], s[8:9], 0, v[0:1]
	v_add_u32_e32 v148, 0, v22
	s_barrier
	s_branch .LBB0_541

; #define PG8_STAGE(bufoff, gbase, voff) do { _Pragma("unroll") for (int _i = 0; _i < 2; ++_i) \
;         __builtin_amdgcn_global_load_lds((const unsigned*)((const char*)(gbase) + (voff)[_i]), (PG8_LAS unsigned*)(lds + (bufoff) + ldsw + _i * 8192), 16, 0, 0); } while (0)
; #define PG8_WAIT_V(n) asm volatile("s_waitcnt vmcnt(" #n ")" ::: "memory")
; #define PG8_BAR __builtin_amdgcn_s_barrier()
; template <class Epi, class Sched, bool ALIGN_EPI = false, bool SP2 = false>
; __device__ __forceinline__ void gemm_phase(PG8_LAS unsigned char* lds, const Gemm g, const Sched& S, const Epi& E) {
;     ...
;     for (int i = 0; i < 2; ++i) { int R, C; stage_rc(tid * 16 + i * 8192, R, C); const int Rb = Epi::PERM ? ((R & ~31) + perm32(R & 31)) : R;
;         voffA[i] = (unsigned)(R * K + C) * 2u; voffB[i] = (unsigned)(Rb * K + C) * 2u; }
;     const size_t kstep = (size_t)(BK * 2);
;     const size_t hstep = (size_t)HALF * K * 2;
;     const size_t tstep = 2 * hstep;
;     const unsigned ldsw = (unsigned)wid * 1024u;
;     const int aoff = lds_byte(wr * 64 + fr, fq * 8), boff = lds_byte(wc * 32 + fr, fq * 8);
;     ...
;     if constexpr (SP2) {
;         PG8_STAGE(PG8_SB(0, 0), cB, voffB); PG8_STAGE(PG8_SB(0, 1), cB + hstep, voffB); PG8_STAGE(PG8_SA(0, 0), cA, voffA); PG8_STAGE(PG8_SA(0, 1), cA + hstep, voffA);
;         if (wr == 1) PG8_BAR;
;         PG8_WAIT_V(2); PG8_BAR;
;         PG8_STAGE(PG8_SB(1, 0), cB + kstep, voffB); PG8_STAGE(PG8_SA(1, 0), cA + kstep, voffA); PG8_STAGE(PG8_SB(1, 1), cB + hstep + kstep, voffB);
;         PG8_WAIT_V(6); PG8_BAR;
.LBB0_573:
	s_lshl_b32 s9, s9, 5
	s_and_b32 s9, s9, 0x60
	s_add_i32 m0, s71, 0x18000
	v_lshl_add_u64 v[8:9], v[8:9], 0, s[34:35]
	s_lshl_b32 s5, s38, 13
	s_lshl_b32 s40, s9, 7
	global_load_lds_dwordx4 v[8:9], off
	v_lshl_add_u64 v[6:7], v[6:7], 0, s[34:35]
	s_add_i32 m0, s71, 0x1a000
	s_add_i32 s77, s71, 0x8000
	s_add_i32 s78, s71, 0xa000
	global_load_lds_dwordx4 v[6:7], off
	v_lshl_add_u64 v[2:3], v[2:3], 0, s[34:35]
	s_mov_b32 m0, s77
	s_add_u32 s38, s46, 0x40080
	global_load_lds_dwordx4 v[2:3], off
	v_lshl_add_u64 v[2:3], v[4:5], 0, s[34:35]
	s_mov_b32 m0, s78
	s_addc_u32 s39, s47, 0
	global_load_lds_dwordx4 v[2:3], off
	s_add_i32 m0, s71, 0x1c000
	v_lshl_add_u64 v[2:3], s[38:39], 0, v[134:135]
	global_load_lds_dwordx4 v[2:3], off
	v_lshl_add_u64 v[2:3], s[38:39], 0, v[130:131]
	s_add_i32 m0, s71, 0x1e000
	v_lshrrev_b32_e32 v1, 1, v1
	global_load_lds_dwordx4 v[2:3], off
	v_or_b32_e32 v33, s4, v12
	v_and_b32_e32 v2, 24, v1
	s_sext_i32_i16 s45, s0
	v_lshlrev_b32_e32 v1, 6, v33
	v_lshlrev_b32_e32 v3, 1, v2
	s_movk_i32 s0, 0x3c0
	v_lshlrev_b32_e32 v4, 2, v33
	v_and_or_b32 v1, v1, s0, v3
	v_and_b32_e32 v4, 32, v4
	s_cmpk_lt_u32 s8, 0x100
	v_bitop3_b32 v4, v1, s5, v4 bitop3:0xde
	v_lshl_or_b32 v1, v12, 6, v3
	v_and_b32_e32 v3, 32, v0
	s_cselect_b64 s[4:5], -1, 0
	s_add_u32 s6, s66, s6
	v_bitop3_b32 v145, v1, s40, v3 bitop3:0xde
	s_addc_u32 s7, s67, s7
	v_mov_b32_e32 v1, v32
	v_lshl_add_u64 v[138:139], s[6:7], 0, v[0:1]
	v_lshlrev_b32_e32 v0, 14, v10
	v_and_b32_e32 v0, 0xffff8000, v0
	v_lshl_add_u32 v0, v11, 11, v0
	v_and_b32_e32 v1, 1, v10
	v_lshl_or_b32 v0, v1, 6, v0
	v_lshl_add_u32 v140, v13, 1, v0
	v_lshlrev_b32_e32 v0, 14, v15
	v_and_b32_e32 v0, 0xffff8000, v0
	s_waitcnt vmcnt(8)
	s_barrier
	s_waitcnt vmcnt(6)
	v_lshl_add_u32 v0, v14, 11, v0
	v_and_b32_e32 v1, 1, v15
	v_lshl_or_b32 v0, v1, 6, v0
	v_or_b32_e32 v147, s9, v2
	v_mov_b32_e32 v141, v32
	v_lshl_add_u32 v142, v16, 1, v0
	v_mov_b32_e32 v143, v32
	s_mov_b32 s0, 0
	v_add_u32_e32 v149, 0, v4
	s_barrier
	s_branch .LBB0_576
